# windowed attention items remapped so one XCD's workgroups take consecutive query blocks of one (batch, kv head): shared K/V rows hit L2
# speedup vs baseline: 1.0056x; 1.0038x over previous
; __global__ void __launch_bounds__(512, 2) fwd_kernel(Args a) {
;     ...
;         { float mqa = fabsf(a.in[4][lane]), mka = fabsf(a.in[5][lane]), mqb = fabsf(a.in[7][lane]), mkb = fabsf(a.in[8][lane]), msk = fabsf(a.in[9][lane & 7]), mr = 0.f;
;           for (int i = tid; i < 8 * 465; i += 512) mr = fmaxf(mr, fabsf(a.in[6][i]));
; #pragma unroll
;           for (int o = 1; o < 64; o <<= 1) { mqa = fmaxf(mqa, __shfl_xor(mqa, o)); mka = fmaxf(mka, __shfl_xor(mka, o)); mqb = fmaxf(mqb, __shfl_xor(mqb, o)); mkb = fmaxf(mkb, __shfl_xor(mkb, o));
;               msk = fmaxf(msk, __shfl_xor(msk, o)); mr = fmaxf(mr, __shfl_xor(mr, o)); }
.Lpbprio_lo:
	s_and_b32 s101, s2, 7
	s_lshl_b32 s101, s101, 5
	s_lshr_b32 s100, s2, 3
	s_or_b32 s101, s101, s100
	s_load_dwordx8 s[4:11], s[74:75], 0x40
	s_waitcnt vmcnt(0)
	v_lshlrev_b32_e32 v0, 2, v191
	s_waitcnt lgkmcnt(0)
	global_load_dword v6, v0, s[84:85]
	global_load_dword v5, v0, s[86:87]
	global_load_dword v3, v0, s[90:91]
	v_lshlrev_b32_e32 v152, 2, v190
	v_mov_b32_e32 v153, 0
	global_load_dword v2, v0, s[4:5]
	v_and_b32_e32 v0, 7, v190
	v_lshlrev_b32_e32 v0, 2, v0
	global_load_dword v4, v0, s[6:7]
	v_add_u32_e32 v7, 0xfffffe00, v190
	v_lshl_add_u64 v[0:1], s[88:89], 0, v[152:153]
	s_mov_b64 s[0:1], 0
	s_mov_b64 s[4:5], 0x800
	s_movk_i32 s6, 0xc87

; template <bool SWA>
; __device__ __forceinline__ void att_load(const AttnP& P, int item, int tid, AttStage<SWA>& st) {
;     constexpr int NCH = SWA ? 6 : 9, KLD = SWA ? 128 : 512;
;     int b, h, x; att_decode<SWA>(item, b, h, x);
;     const int tb = b * SEQ, kcol = h * 64;
;     const bf16_t* Kp = SWA ? P.KB : P.KA; const bf16_t* VT = SWA ? P.VBT : P.VAT;
;     const int base = SWA ? 128 * x - 128 : min(max(2 * x - 4, 0), 56);
; #pragma unroll
;     for (int i = 0; i < NCH; ++i) {
;         const int idx = tid + 512 * i;
;         { const int k = idx >> 3, c = idx & 7; int tok;
;           if (SWA) tok = min(max(base + k, 0), SEQ - 1); else tok = min(base + (k >> 6), 63) * 64 + (k & 63);
;           st.k[i] = *(const u32x4*)(Kp + (size_t)(tb + tok) * KLD + kcol + 8 * c); }
;         { const int kb = idx >> 6, d = idx & 63; int tok;
;           if (SWA) tok = min(max(base + 8 * kb, 0), SEQ - 8); else tok = min(base + (kb >> 3), 63) * 64 + 8 * (kb & 7);
;           st.v[i] = *(const u32x4*)(VT + ((size_t)((tb + tok) >> 3) * KLD + kcol + d) * 8); }
;     }
; }
; template <bool SWA>
; __device__ __forceinline__ void att_load_qz(const AttnP& P, int lane, int tb, int qpos0, int hq, AttQZ& o) {
;     const int li = lane & 15, fq = lane >> 4;
;     const bf16_t* Q = SWA ? P.QB : P.QA; const bf16_t* Z = SWA ? P.ZB : P.ZA;
;     const bf16_t* qrow = Q + (size_t)(tb + qpos0 + li) * 512 + hq * 64 + 8 * fq;
;     o.q0 = *(const bf16x8*)qrow; o.q1 = *(const bf16x8*)(qrow + 32);
;     const bf16_t* zrow = Z + (size_t)(tb + qpos0 + li) * 512 + hq * 64 + 8 * fq;
; #pragma unroll
;     for (int hh = 0; hh < 2; ++hh) o.z[hh] = *(const u32x4*)(zrow + 32 * hh);
.LBB0_351:
	s_cmpk_gt_i32 s2, 0x2ff
	s_waitcnt lgkmcnt(0)
	s_barrier
	s_cbranch_scc1 .LBB0_354
	s_lshl_b32 s1, s101, 1
	s_and_b32 s7, s1, 64
	s_lshl_b32 s1, s101, 7
	s_and_b32 s8, s1, 0xf80
	s_add_i32 s9, s8, 0xffffff80
	v_lshrrev_b32_e32 v36, 3, v190
	s_lshl_b32 s0, s101, 6
	v_or_b32_e32 v0, s9, v36
	v_mov_b32_e32 v1, 0xfff
	s_and_b32 s0, s0, 0xfffff000
	s_lshl_b32 s4, s7, 1
	v_med3_i32 v0, v0, 0, v1
	s_add_u32 s4, s18, s4
	v_or_b32_e32 v0, s0, v0
	s_addc_u32 s5, s19, 0
	v_and_b32_e32 v40, 0x70, v89
	v_mov_b32_e32 v41, 0
	v_ashrrev_i32_e32 v1, 31, v0
	v_lshl_add_u64 v[42:43], s[4:5], 0, v[40:41]
	v_lshlrev_b64 v[0:1], 8, v[0:1]
	v_lshl_add_u64 v[8:9], v[42:43], 0, v[0:1]
	v_and_b32_e32 v0, 0x78, v36
	v_or_b32_e32 v0, s9, v0
	v_mov_b32_e32 v1, 0xff8
	v_med3_i32 v0, v0, 0, v1
	v_or_b32_e32 v0, s0, v0
	v_ashrrev_i32_e32 v0, 3, v0
	v_ashrrev_i32_e32 v1, 31, v0
	v_readlane_b32 s10, v249, 11
	v_or_b32_e32 v2, s7, v191
	v_lshlrev_b64 v[0:1], 11, v[0:1]
	v_readlane_b32 s11, v249, 12
	v_lshlrev_b32_e32 v40, 4, v2
	s_movk_i32 s4, 0x178
	v_lshl_add_u64 v[0:1], s[10:11], 0, v[0:1]
	v_lshl_add_u64 v[10:11], v[0:1], 0, v[40:41]
	global_load_dwordx4 v[0:3], v[8:9], off
	global_load_dwordx4 v[4:7], v[10:11], off
	v_add_u32_e32 v8, 0x200, v190
	v_lshrrev_b32_e32 v10, 3, v8
	v_add_u32_e32 v8, s9, v10
	v_max_i32_e32 v8, 0, v8
	v_or_b32_e32 v8, s0, v8
	v_ashrrev_i32_e32 v9, 31, v8
	v_lshlrev_b64 v[8:9], 8, v[8:9]
	v_lshl_add_u64 v[16:17], v[42:43], 0, v[8:9]
	v_and_b32_e32 v8, 0xf8, v10
	v_add_u32_e32 v8, s9, v8
	v_max_i32_e32 v8, 0, v8
	v_or_b32_e32 v8, s0, v8
	v_ashrrev_i32_e32 v8, 3, v8
	v_ashrrev_i32_e32 v9, 31, v8
	v_lshlrev_b64 v[8:9], 11, v[8:9]
	v_lshl_add_u64 v[8:9], s[10:11], 0, v[8:9]
	v_lshl_add_u64 v[18:19], v[8:9], 0, v[40:41]
	global_load_dwordx4 v[8:11], v[16:17], off
	global_load_dwordx4 v[12:15], v[18:19], off
	v_or_b32_e32 v16, s0, v36
	v_add_u32_e32 v16, s9, v16
	v_add_u32_e32 v16, 0x80, v16
	v_ashrrev_i32_e32 v17, 31, v16
	v_lshlrev_b64 v[18:19], 8, v[16:17]
	v_ashrrev_i32_e32 v16, 3, v16
	v_ashrrev_i32_e32 v17, 31, v16
	v_lshlrev_b64 v[16:17], 11, v[16:17]
	v_lshl_add_u64 v[24:25], v[42:43], 0, v[18:19]
	v_lshl_add_u64 v[16:17], s[10:11], 0, v[16:17]
	v_lshl_add_u64 v[26:27], v[16:17], 0, v[40:41]
	global_load_dwordx4 v[16:19], v[24:25], off
	global_load_dwordx4 v[20:23], v[26:27], off
	v_add_u32_e32 v24, 0x600, v190
	v_lshrrev_b32_e32 v26, 3, v24
	v_add_u32_e32 v24, s9, v26
	v_min_u32_e32 v24, 0xfff, v24
	v_or_b32_e32 v24, s0, v24
	v_ashrrev_i32_e32 v25, 31, v24
	v_lshlrev_b64 v[24:25], 8, v[24:25]
	v_lshl_add_u64 v[32:33], v[42:43], 0, v[24:25]
	v_and_b32_e32 v24, 0x1f8, v26
	v_add_u32_e32 v24, s9, v24
	v_min_u32_e32 v24, 0xff8, v24
	v_or_b32_e32 v24, s0, v24
	v_ashrrev_i32_e32 v24, 3, v24
	v_ashrrev_i32_e32 v25, 31, v24
	v_lshlrev_b64 v[24:25], 11, v[24:25]
	v_lshl_add_u64 v[24:25], s[10:11], 0, v[24:25]
	v_lshl_add_u64 v[34:35], v[24:25], 0, v[40:41]
	global_load_dwordx4 v[24:27], v[32:33], off
	global_load_dwordx4 v[28:31], v[34:35], off
	v_or_b32_e32 v32, 0x100, v36
	v_add_u32_e32 v32, s9, v32
	v_min_u32_e32 v32, 0xfff, v32
	v_or_b32_e32 v32, s0, v32
	v_ashrrev_i32_e32 v33, 31, v32
	v_lshlrev_b64 v[32:33], 8, v[32:33]
	v_lshl_add_u64 v[44:45], v[42:43], 0, v[32:33]
	v_mov_b32_e32 v32, 0x100
	v_bitop3_b32 v32, v36, s4, v32 bitop3:0xc8
	v_add_u32_e32 v32, s9, v32
	v_min_u32_e32 v32, 0xff8, v32
	v_or_b32_e32 v32, s0, v32
	v_ashrrev_i32_e32 v32, 3, v32
	v_ashrrev_i32_e32 v33, 31, v32
	v_lshlrev_b64 v[32:33], 11, v[32:33]
	v_lshl_add_u64 v[32:33], s[10:11], 0, v[32:33]
	v_lshl_add_u64 v[46:47], v[32:33], 0, v[40:41]
	global_load_dwordx4 v[32:35], v[44:45], off
	global_load_dwordx4 v[36:39], v[46:47], off
	v_add_u32_e32 v44, 0xa00, v190
	v_lshrrev_b32_e32 v46, 3, v44
	v_add_u32_e32 v44, s9, v46
	v_min_u32_e32 v44, 0xfff, v44
	v_or_b32_e32 v44, s0, v44
	v_ashrrev_i32_e32 v45, 31, v44
	v_lshlrev_b64 v[44:45], 8, v[44:45]
	v_lshl_add_u64 v[42:43], v[42:43], 0, v[44:45]
	v_and_b32_e32 v44, 0x1f8, v46
	v_add_u32_e32 v44, s9, v44
	v_min_u32_e32 v44, 0xff8, v44
	v_or_b32_e32 v44, s0, v44
	v_ashrrev_i32_e32 v44, 3, v44
	v_ashrrev_i32_e32 v45, 31, v44
	v_lshlrev_b64 v[44:45], 11, v[44:45]
	v_lshl_add_u64 v[44:45], s[10:11], 0, v[44:45]
	v_lshl_add_u64 v[52:53], v[44:45], 0, v[40:41]
	v_and_or_b32 v40, v190, 15, s8
	v_or_b32_e32 v40, s0, v40
	global_load_dwordx4 v[44:47], v[42:43], off
	global_load_dwordx4 v[48:51], v[52:53], off
	v_lshl_add_u32 v42, s3, 4, v40
	v_ashrrev_i32_e32 v43, 31, v42
	v_readlane_b32 s4, v249, 13
	v_lshlrev_b64 v[42:43], 10, v[42:43]
	v_readlane_b32 s5, v249, 14
	s_lshl_b32 s0, s101, 4
	s_mov_b32 s1, 0
	v_lshl_add_u64 v[52:53], s[4:5], 0, v[42:43]
	v_readlane_b32 s4, v249, 15
	v_readlane_b32 s5, v249, 16
	s_and_b32 s0, s0, 0x200
	v_and_b32_e32 v40, 24, v88
	v_lshl_add_u64 v[42:43], s[4:5], 0, v[42:43]
	v_lshl_add_u64 v[52:53], v[52:53], 0, s[0:1]
	v_lshlrev_b32_e32 v40, 1, v40
	v_lshl_add_u64 v[42:43], v[42:43], 0, s[0:1]
	v_lshl_add_u64 v[52:53], v[52:53], 0, v[40:41]
	v_lshl_add_u64 v[72:73], v[42:43], 0, v[40:41]
	global_load_dwordx4 v[64:67], v[52:53], off
	global_load_dwordx4 v[68:71], v[52:53], off offset:64
	s_nop 0
	global_load_dwordx4 v[52:55], v[72:73], off
	global_load_dwordx4 v[40:43], v[72:73], off offset:64
	s_bfe_u32 s4, s48, 0x20006
	s_cmp_lt_i32 s4, 1
	s_mov_b32 s31, s4
	s_cbranch_scc0 .LBB0_355
	s_branch .LBB0_359

; #define LAS __attribute__((address_space(3)))
; template <bool SWA>
; __device__ __forceinline__ void att_load(const AttnP& P, int item, int tid, AttStage<SWA>& st) {
;     constexpr int NCH = SWA ? 6 : 9, KLD = SWA ? 128 : 512;
;     int b, h, x; att_decode<SWA>(item, b, h, x);
;     const int tb = b * SEQ, kcol = h * 64;
;     const bf16_t* Kp = SWA ? P.KB : P.KA; const bf16_t* VT = SWA ? P.VBT : P.VAT;
;     const int base = SWA ? 128 * x - 128 : min(max(2 * x - 4, 0), 56);
; #pragma unroll
;     for (int i = 0; i < NCH; ++i) {
;         const int idx = tid + 512 * i;
;         { const int k = idx >> 3, c = idx & 7; int tok;
;           if (SWA) tok = min(max(base + k, 0), SEQ - 1); else tok = min(base + (k >> 6), 63) * 64 + (k & 63);
;           st.k[i] = *(const u32x4*)(Kp + (size_t)(tb + tok) * KLD + kcol + 8 * c); }
;         { const int kb = idx >> 6, d = idx & 63; int tok;
;           if (SWA) tok = min(max(base + 8 * kb, 0), SEQ - 8); else tok = min(base + (kb >> 3), 63) * 64 + 8 * (kb & 7);
;           st.v[i] = *(const u32x4*)(VT + ((size_t)((tb + tok) >> 3) * KLD + kcol + d) * 8); }
;     }
; }
; template <bool SWA>
; __device__ __forceinline__ void att_phase(const AttnP& P, LAS unsigned char* lds, int tid, int wave, int lane, bool fast, float shift, AttStage<SWA>& st, AttQZ& qzn, bool pre) {
;     constexpr int NITEMS = SWA ? 768 : 3072;
;     int item = blockIdx.x;
;     ...
;     if (!pre && item < NITEMS) { int b, h, x; att_decode<SWA>(item, b, h, x); att_load<SWA>(P, item, tid, st); att_load_qz<SWA>(P, lane, b * SEQ, ATT_QPOS(x), SWA ? 4 * h : h, qzn); }
.LBB0_364:
	s_cmpk_lt_i32 s42, 0xc00
	s_cselect_b64 s[0:1], -1, 0
	s_cmpk_gt_i32 s2, 0x2ff
	s_cselect_b64 s[4:5], -1, 0
	s_or_b64 s[0:1], s[4:5], s[0:1]
	s_and_b64 vcc, exec, s[0:1]
	s_cbranch_vccnz .LBB0_366
	s_lshl_b32 s1, s101, 1
	s_and_b32 s6, s1, 64
	s_lshl_b32 s1, s101, 7
	s_and_b32 s7, s1, 0xf80
	s_add_i32 s8, s7, 0xffffff80
	v_lshlrev_b32_e32 v0, 4, v190
	v_lshrrev_b32_e32 v36, 3, v190
	s_lshl_b32 s0, s101, 6
	s_waitcnt vmcnt(1)
	v_and_b32_e32 v40, 0x70, v0
	v_or_b32_e32 v0, s8, v36
	v_mov_b32_e32 v1, 0xfff
	s_and_b32 s0, s0, 0xfffff000
	s_lshl_b32 s4, s6, 1
	v_med3_i32 v0, v0, 0, v1
	s_add_u32 s4, s18, s4
	v_or_b32_e32 v0, s0, v0
	s_addc_u32 s5, s19, 0
	v_mov_b32_e32 v41, 0
	v_ashrrev_i32_e32 v1, 31, v0
	v_lshl_add_u64 v[42:43], s[4:5], 0, v[40:41]
	v_lshlrev_b64 v[0:1], 8, v[0:1]
	v_lshl_add_u64 v[8:9], v[42:43], 0, v[0:1]
	v_and_b32_e32 v0, 0x78, v36
	v_or_b32_e32 v0, s8, v0
	v_mov_b32_e32 v1, 0xff8
	v_med3_i32 v0, v0, 0, v1
	v_or_b32_e32 v0, s0, v0
	v_ashrrev_i32_e32 v0, 3, v0
	v_ashrrev_i32_e32 v1, 31, v0
	v_readlane_b32 s10, v249, 11
	v_or_b32_e32 v2, s6, v191
	v_lshlrev_b64 v[0:1], 11, v[0:1]
	v_readlane_b32 s11, v249, 12
	v_lshlrev_b32_e32 v40, 4, v2
	s_movk_i32 s4, 0x178
	v_lshl_add_u64 v[0:1], s[10:11], 0, v[0:1]
	v_lshl_add_u64 v[10:11], v[0:1], 0, v[40:41]
	global_load_dwordx4 v[0:3], v[8:9], off
	global_load_dwordx4 v[4:7], v[10:11], off
	v_add_u32_e32 v8, 0x200, v190
	v_lshrrev_b32_e32 v10, 3, v8
	v_add_u32_e32 v8, s8, v10
	v_max_i32_e32 v8, 0, v8
	v_or_b32_e32 v8, s0, v8
	v_ashrrev_i32_e32 v9, 31, v8
	v_lshlrev_b64 v[8:9], 8, v[8:9]
	v_lshl_add_u64 v[16:17], v[42:43], 0, v[8:9]
	v_and_b32_e32 v8, 0xf8, v10
	v_add_u32_e32 v8, s8, v8
	v_max_i32_e32 v8, 0, v8
	v_or_b32_e32 v8, s0, v8
	v_ashrrev_i32_e32 v8, 3, v8
	v_ashrrev_i32_e32 v9, 31, v8
	v_lshlrev_b64 v[8:9], 11, v[8:9]
	v_lshl_add_u64 v[8:9], s[10:11], 0, v[8:9]
	v_lshl_add_u64 v[18:19], v[8:9], 0, v[40:41]
	global_load_dwordx4 v[8:11], v[16:17], off
	global_load_dwordx4 v[12:15], v[18:19], off
	v_or_b32_e32 v16, s0, v36
	v_add_u32_e32 v16, s8, v16
	v_add_u32_e32 v16, 0x80, v16
	v_ashrrev_i32_e32 v17, 31, v16
	v_lshlrev_b64 v[18:19], 8, v[16:17]
	v_ashrrev_i32_e32 v16, 3, v16
	v_ashrrev_i32_e32 v17, 31, v16
	v_lshlrev_b64 v[16:17], 11, v[16:17]
	v_lshl_add_u64 v[24:25], v[42:43], 0, v[18:19]
	v_lshl_add_u64 v[16:17], s[10:11], 0, v[16:17]
	v_lshl_add_u64 v[26:27], v[16:17], 0, v[40:41]
	global_load_dwordx4 v[16:19], v[24:25], off
	global_load_dwordx4 v[20:23], v[26:27], off
	v_add_u32_e32 v24, 0x600, v190
	v_lshrrev_b32_e32 v26, 3, v24
	v_add_u32_e32 v24, s8, v26
	v_min_u32_e32 v24, 0xfff, v24
	v_or_b32_e32 v24, s0, v24
	v_ashrrev_i32_e32 v25, 31, v24
	v_lshlrev_b64 v[24:25], 8, v[24:25]
	v_lshl_add_u64 v[32:33], v[42:43], 0, v[24:25]
	v_and_b32_e32 v24, 0x1f8, v26
	v_add_u32_e32 v24, s8, v24
	v_min_u32_e32 v24, 0xff8, v24
	v_or_b32_e32 v24, s0, v24
	v_ashrrev_i32_e32 v24, 3, v24
	v_ashrrev_i32_e32 v25, 31, v24
	v_lshlrev_b64 v[24:25], 11, v[24:25]
	v_lshl_add_u64 v[24:25], s[10:11], 0, v[24:25]
	v_lshl_add_u64 v[34:35], v[24:25], 0, v[40:41]
	global_load_dwordx4 v[24:27], v[32:33], off
	global_load_dwordx4 v[28:31], v[34:35], off
	v_or_b32_e32 v32, 0x100, v36
	v_add_u32_e32 v32, s8, v32
	v_min_u32_e32 v32, 0xfff, v32
	v_or_b32_e32 v32, s0, v32
	v_ashrrev_i32_e32 v33, 31, v32
	v_lshlrev_b64 v[32:33], 8, v[32:33]
	v_lshl_add_u64 v[44:45], v[42:43], 0, v[32:33]
	v_mov_b32_e32 v32, 0x100
	v_bitop3_b32 v32, v36, s4, v32 bitop3:0xc8
	v_add_u32_e32 v32, s8, v32
	v_min_u32_e32 v32, 0xff8, v32
	v_or_b32_e32 v32, s0, v32
	v_ashrrev_i32_e32 v32, 3, v32
	v_ashrrev_i32_e32 v33, 31, v32
	v_lshlrev_b64 v[32:33], 11, v[32:33]
	v_lshl_add_u64 v[32:33], s[10:11], 0, v[32:33]
	v_lshl_add_u64 v[46:47], v[32:33], 0, v[40:41]
	global_load_dwordx4 v[32:35], v[44:45], off
	global_load_dwordx4 v[36:39], v[46:47], off
	v_add_u32_e32 v44, 0xa00, v190
	v_lshrrev_b32_e32 v46, 3, v44
	v_add_u32_e32 v44, s8, v46
	v_min_u32_e32 v44, 0xfff, v44
	v_or_b32_e32 v44, s0, v44
	v_ashrrev_i32_e32 v45, 31, v44
	v_lshlrev_b64 v[44:45], 8, v[44:45]
	v_lshl_add_u64 v[42:43], v[42:43], 0, v[44:45]
	v_and_b32_e32 v44, 0x1f8, v46
	v_add_u32_e32 v44, s8, v44
	v_min_u32_e32 v44, 0xff8, v44
	v_or_b32_e32 v44, s0, v44
	v_ashrrev_i32_e32 v44, 3, v44
	v_ashrrev_i32_e32 v45, 31, v44
	v_lshlrev_b64 v[44:45], 11, v[44:45]
	v_lshl_add_u64 v[44:45], s[10:11], 0, v[44:45]
	v_lshl_add_u64 v[52:53], v[44:45], 0, v[40:41]
	v_and_or_b32 v40, v190, 15, s7
	v_or_b32_e32 v40, s0, v40
	global_load_dwordx4 v[44:47], v[42:43], off
	global_load_dwordx4 v[48:51], v[52:53], off
	v_lshl_add_u32 v42, s3, 4, v40
	v_ashrrev_i32_e32 v43, 31, v42
	v_readlane_b32 s4, v249, 13
	v_lshlrev_b64 v[42:43], 10, v[42:43]
	v_readlane_b32 s5, v249, 14
	s_lshl_b32 s0, s101, 4
	s_mov_b32 s1, 0
	v_lshl_add_u64 v[52:53], s[4:5], 0, v[42:43]
	v_readlane_b32 s4, v249, 15
	v_readlane_b32 s5, v249, 16
	s_and_b32 s0, s0, 0x200
	v_lshl_add_u64 v[52:53], v[52:53], 0, s[0:1]
	v_lshl_add_u64 v[42:43], s[4:5], 0, v[42:43]
	v_and_b32_e32 v40, 48, v190
	v_lshl_add_u64 v[42:43], v[42:43], 0, s[0:1]
	v_lshl_add_u64 v[52:53], v[52:53], 0, v[40:41]
	v_lshl_add_u64 v[56:57], v[42:43], 0, v[40:41]
	global_load_dwordx4 v[64:67], v[52:53], off
	global_load_dwordx4 v[68:71], v[52:53], off offset:64
	s_nop 0
	global_load_dwordx4 v[52:55], v[56:57], off
	global_load_dwordx4 v[40:43], v[56:57], off offset:64
; #define LAS __attribute__((address_space(3)))
; template <bool SWA>
; __device__ __forceinline__ void att_phase(const AttnP& P, LAS unsigned char* lds, int tid, int wave, int lane, bool fast, float shift, AttStage<SWA>& st, AttQZ& qzn, bool pre) {
;     constexpr int NITEMS = SWA ? 768 : 3072;
;     int item = blockIdx.x;
;     ...
;     if (!pre && item < NITEMS) { int b, h, x; att_decode<SWA>(item, b, h, x); att_load<SWA>(P, item, tid, st); att_load_qz<SWA>(P, lane, b * SEQ, ATT_QPOS(x), SWA ? 4 * h : h, qzn); }
;     for (; item < NITEMS; item += gridDim.x) {
;         int b, h, x; att_decode<SWA>(item, b, h, x);
;         att_store<SWA>(lds, tid, st);
;         if (!SWA) { if (tid < 465) ((LAS float*)(lds + ATT_RPB))[tid] = P.rpb[h * 465 + tid] * LOG2E; }
;         __syncthreads();
;         const int nitem = item + (int)gridDim.x; const bool has_next = nitem < NITEMS;
;         int nb = 0, nh = 0, nx = 0; if (has_next) { att_decode<SWA>(nitem, nb, nh, nx); att_load<SWA>(P, nitem, tid, st); }
;         const int tb = b * SEQ;
;         if (SWA) {
; #pragma unroll 1
;             for (int j = 0; j < 4; ++j) { int kl = 16 * wave; asm volatile("" : "+v"(kl));
;                 const AttQZ qz = qzn;
;                 if (j < 3) att_load_qz<true>(P, lane, tb, ATT_QPOS(x), 4 * h + j + 1, qzn);
;                 else if (has_next) att_load_qz<true>(P, lane, nb * SEQ, ATT_QPOS(nx), 4 * nh, qzn);
;                 if (fast) att_tile<true, true>(P, lds, lane, tb, 128 * x + 16 * wave, 4 * h + j, kl, 0, 0, 0, 0, qz, shift);
;                 else att_tile<true, false>(P, lds, lane, tb, 128 * x + 16 * wave, 4 * h + j, kl, 0, 0, 0, 0, qz, 0.f); }
.LBB0_366:
	s_cmpk_gt_i32 s2, 0x2ff
	s_cbranch_scc1 .LBB0_427
	s_waitcnt vmcnt(2)
	v_lshlrev_b32_e32 v61, 4, v190
	s_movk_i32 s0, 0x70
	s_waitcnt vmcnt(1)
	v_bitop3_b32 v56, v61, s0, v190 bitop3:0x48
	v_lshrrev_b32_e32 v57, 1, v190
	v_add_u32_e32 v63, 0, v56
	v_and_b32_e32 v56, 16, v152
	v_and_b32_e32 v58, 12, v57
	v_or3_b32 v56, v56, v153, v58
	s_movk_i32 s0, 0x3c0
	v_and_or_b32 v58, v190, s0, v56
	v_lshlrev_b32_e32 v73, 4, v58
	v_add_u32_e32 v58, 0x200, v190
	v_lshlrev_b32_e32 v59, 4, v58
	s_movk_i32 s0, 0x7c0
	v_and_b32_e32 v74, 0x7f80, v59
	v_and_or_b32 v59, v58, s0, v56
	v_lshlrev_b32_e32 v75, 4, v59
	v_or_b32_e32 v59, 0x400, v190
	v_lshlrev_b32_e32 v60, 4, v59
	v_and_or_b32 v59, v59, s0, v56
	v_lshlrev_b32_e32 v77, 4, v59
	v_add_u32_e32 v59, 0x600, v190
	v_writelane_b32 v249, s72, 17
	v_and_b32_e32 v76, 0x7f80, v60
	v_lshlrev_b32_e32 v60, 4, v59
	s_movk_i32 s0, 0xfc0
	v_writelane_b32 v249, s73, 18
	v_and_b32_e32 v78, 0xff80, v60
	v_and_or_b32 v60, v59, s0, v56
	v_writelane_b32 v249, s94, 19
	v_lshlrev_b32_e32 v79, 4, v60
	v_or_b32_e32 v60, 0x800, v190
	s_movk_i32 s1, 0xbc0
	v_writelane_b32 v249, s95, 20
	v_lshlrev_b32_e32 v62, 4, v60
	v_and_or_b32 v60, v60, s1, v56
	v_writelane_b32 v249, s92, 21
	v_lshlrev_b32_e32 v81, 4, v60
	v_add_u32_e32 v60, 0xa00, v190
	v_lshlrev_b32_e32 v199, 2, v183
	v_writelane_b32 v249, s93, 22
	v_and_b32_e32 v80, 0xbf80, v62
	v_lshlrev_b32_e32 v62, 4, v60
	v_and_b32_e32 v196, 15, v190
	v_or_b32_e32 v203, 0x60, v199
	v_writelane_b32 v249, s74, 23
	v_and_b32_e32 v82, 0xff80, v62
	s_lshl_b32 s4, s3, 4
	v_sub_u32_e32 v62, v203, v196
	s_movk_i32 s3, 0x6f
	v_writelane_b32 v249, s75, 24
	v_cmp_gt_u32_e64 s[6:7], s3, v62
	s_movk_i32 s3, 0x6e
	v_and_b32_e32 v72, 0x3f80, v61
	v_writelane_b32 v249, s6, 25
	v_and_b32_e32 v164, 0x70, v61
	v_or_b32_e32 v61, 0x80, v199
	v_writelane_b32 v249, s7, 26
	v_cmp_gt_u32_e64 s[6:7], s3, v62
	v_sub_u32_e32 v61, v61, v196
	s_movk_i32 s3, 0x81
	v_writelane_b32 v249, s6, 27
	s_movk_i32 s1, 0x80
	v_exp_f32_e32 v168, 0xf149f2ca
	v_writelane_b32 v249, s7, 28
	v_cmp_gt_u32_e64 s[6:7], s3, v61
	v_and_or_b32 v56, v60, s0, v56
	v_lshlrev_b32_e32 v83, 4, v56
	v_writelane_b32 v249, s6, 29
	v_lshrrev_b32_e32 v184, 3, v190
	s_movk_i32 s0, 0x178
	v_writelane_b32 v249, s7, 30
	v_cmp_gt_u32_e64 s[6:7], s1, v61
	s_movk_i32 s1, 0x7f
	v_mov_b32_e32 v56, 0x100
	v_writelane_b32 v249, s6, 31
	v_mov_b32_e32 v165, 0
	v_lshrrev_b32_e32 v186, 3, v58
	v_writelane_b32 v249, s7, 32
	v_cmp_gt_u32_e64 s[6:7], s1, v61
	s_movk_i32 s1, 0x7e
	v_lshrrev_b32_e32 v188, 3, v59
	v_writelane_b32 v249, s6, 33
	v_bitop3_b32 v193, v184, s0, v56 bitop3:0xc8
	v_lshrrev_b32_e32 v194, 3, v60
	v_writelane_b32 v249, s7, 34
	v_cmp_gt_u32_e64 s[6:7], s1, v61
	v_and_b32_e32 v60, 24, v57
	s_add_i32 s0, 0, 0x12000
	v_writelane_b32 v249, s6, 35
	v_xor_b32_e32 v56, 0x80000000, v182
	v_lshl_add_u64 v[166:167], s[18:19], 0, v[164:165]
	v_writelane_b32 v249, s7, 36
	v_and_b32_e32 v164, 48, v190
	v_readlane_b32 s1, v249, 8
	s_lshl_b32 s3, s1, 6
	v_writelane_b32 v249, s3, 37
	s_lshl_b32 s1, s1, 7
	v_writelane_b32 v249, s1, 38
	s_mov_b32 s39, 0
	v_and_b32_e32 v185, 0x78, v184
	v_and_b32_e32 v187, 0xf8, v186
	v_and_b32_e32 v189, 0x1f8, v188
	v_or_b32_e32 v192, 0x100, v184
	v_and_b32_e32 v195, 0x1f8, v194
	v_or_b32_e32 v197, s4, v196
	v_or_b32_e32 v198, 4, v183
	v_lshl_add_u32 v200, v196, 4, s0
	v_mov_b32_e32 v57, v56
	v_mov_b32_e32 v58, v56
	v_mov_b32_e32 v59, v56
	v_or_b32_e32 v201, 32, v199
	v_or_b32_e32 v202, 64, v199
	v_or_b32_e32 v204, 0x80, v184
	v_mov_b32_e32 v169, v168
	v_cvt_pk_bf16_f32 v62, v168, v168
	s_lshl_b32 s5, s101, 6
	s_lshl_b32 s8, s101, 7
	v_lshl_add_u64 v[170:171], s[64:65], 0, v[164:165]
	v_add_u32_e32 v205, v63, v72
	v_add_u32_e32 v206, s0, v73
	v_add_u32_e32 v207, v63, v74
	v_add_u32_e32 v208, s0, v75
	v_add_u32_e32 v209, v63, v76
	v_add_u32_e32 v210, s0, v77
	v_add_u32_e32 v211, v63, v78
	v_add_u32_e32 v212, s0, v79
	v_add_u32_e32 v213, v63, v80
	v_add_u32_e32 v214, s0, v81
	v_add_u32_e32 v215, v63, v82
	v_add_u32_e32 v216, s0, v83
	s_movk_i32 s33, 0x101
	v_writelane_b32 v249, s4, 39
	v_mov_b32_e32 v217, s4
	v_lshlrev_b32_e32 v164, 1, v60
	v_mov_b32_e32 v218, 0xfff
	v_mov_b32_e32 v219, 0xff8
	v_mov_b32_e32 v220, 0xf149f2ca
	s_mov_b32 s0, s101
	v_writelane_b32 v249, s2, 40
	s_branch .LBB0_369
